# NA key-row loop: counted vmcnt waits (distance-2 K/V prefetch actually in flight)
# speedup vs baseline: 1.0065x; 1.0065x over previous
.LBB0_298:
	s_ashr_i32 s27, s45, 7
	s_and_b64 s[16:17], s[20:21], exec
	s_cselect_b32 s16, s36, s27
	s_ashr_i32 s17, s16, 31
	s_lshl_b64 s[30:31], s[16:17], 12
	s_lshl_b32 s17, s47, 6
	s_waitcnt vmcnt(0)
	v_or_b32_e32 v0, s17, v83
	s_lshl_b32 s27, s53, 1
	v_or_b32_e32 v0, s30, v0
	v_mad_u64_u32 v[8:9], s[28:29], v0, s43, v[86:87]
	v_add_lshl_u32 v0, v109, s27, 6
	v_add_lshl_u32 v10, v110, s27, 6
	v_ashrrev_i32_e32 v1, 31, v0
	v_ashrrev_i32_e32 v11, 31, v10
	v_mad_i32_i24 v9, s31, v159, v9
	v_lshlrev_b64 v[98:99], 1, v[0:1]
	v_lshlrev_b64 v[100:101], 1, v[10:11]
	v_lshl_add_u64 v[4:5], v[8:9], 0, v[98:99]
	v_lshl_add_u64 v[8:9], v[8:9], 0, v[100:101]
	global_load_dwordx4 v[0:3], v[4:5], off offset:1024
	s_nop 0
	global_load_dwordx4 v[4:7], v[4:5], off offset:2048
	s_nop 0
	global_load_dwordx4 v[16:19], v[8:9], off offset:1024
	global_load_dwordx4 v[28:31], v[8:9], off offset:2048
	s_sub_i32 s56, s52, s47
	v_or_b32_e32 v8, s17, v106
	s_lshl_b32 s17, s51, 6
	s_add_i32 s29, s27, s37
	s_add_i32 s28, s56, 8
	s_ashr_i32 s27, s17, 31
	s_add_u32 s17, s30, s17
	v_or_b32_e32 v8, s30, v8
	s_addc_u32 s51, s31, s27
	v_or_b32_e32 v38, s17, v82
	s_lshl_b32 s27, s29, 6
	s_lshl_b32 s17, s29, 7
	v_mad_u64_u32 v[20:21], s[52:53], v8, s43, v[86:87]
	s_add_u32 s30, s60, s17
	v_mad_i32_i24 v21, s31, v159, v21
	s_addc_u32 s31, s61, 0
	v_lshl_add_u64 v[12:13], v[20:21], 0, v[98:99]
	v_lshl_add_u64 v[20:21], v[20:21], 0, v[100:101]
	v_or_b32_e32 v96, s38, v38
	v_mov_b64_e32 v[36:37], s[30:31]
	v_or_b32_e32 v94, s42, v38
	global_load_dwordx4 v[8:11], v[12:13], off offset:1024
	s_nop 0
	global_load_dwordx4 v[12:15], v[12:13], off offset:2048
	s_nop 0
	global_load_dwordx4 v[32:35], v[20:21], off offset:1024
	global_load_dwordx4 v[48:51], v[20:21], off offset:2048
	v_mad_u64_u32 v[20:21], s[30:31], v96, s43, v[36:37]
	v_mad_u64_u32 v[36:37], s[30:31], v94, s43, v[36:37]
	v_mad_i32_i24 v21, s51, v159, v21
	v_mad_i32_i24 v37, s51, v159, v37
	v_lshl_add_u64 v[24:25], v[20:21], 0, v[92:93]
	v_lshl_add_u64 v[40:41], v[36:37], 0, v[92:93]
	global_load_dwordx4 v[20:23], v[24:25], off
	s_nop 0
	global_load_dwordx4 v[24:27], v[24:25], off offset:64
	s_nop 0
	global_load_dwordx4 v[36:39], v[40:41], off
	s_nop 0
	global_load_dwordx4 v[40:43], v[40:41], off offset:64
	s_mul_i32 s17, s47, 0x7c
	s_mul_i32 s52, s48, 0xf8
	s_add_i32 s29, s56, 5
	s_add_i32 s30, s56, 6
	s_add_i32 s31, s24, 8
	s_add_i32 s48, s17, 0
	s_cmp_lt_u32 s50, 56
	s_cselect_b32 s50, s50, 56
	v_mov_b32_e32 v97, s51
	v_mov_b32_e32 v95, s51
	s_mul_hi_i32 s17, s16, 0x1400000
	s_mul_i32 s16, s16, 0x1400000
	s_mul_hi_u32 s51, s50, 0x50000
	s_mul_i32 s50, s50, 0x50000
	s_add_u32 s16, s16, s50
	s_addc_u32 s17, s17, s51
	v_lshl_add_u64 v[104:105], v[90:91], 0, s[16:17]
	s_add_i32 s16, s44, s47
	s_sub_i32 s16, s16, s49
	v_mov_b32_e32 v64, v84
	v_mov_b32_e32 v65, v84
	v_mov_b32_e32 v66, v84
	v_mov_b32_e32 v67, v84
	s_mulk_i32 s16, 0x7c
	v_mov_b32_e32 v85, v84
	v_mov_b64_e32 v[78:79], v[66:67]
	v_mov_b64_e32 v[74:75], v[66:67]
	v_mov_b64_e32 v[70:71], v[66:67]
	v_mov_b64_e32 v[60:61], v[64:65]
	v_mov_b64_e32 v[56:57], v[64:65]
	v_mov_b64_e32 v[52:53], v[64:65]
	v_mov_b64_e32 v[44:45], v[64:65]
	v_subrev_u32_e32 v161, s52, v125
	v_subrev_u32_e32 v162, s52, v126
	v_subrev_u32_e32 v163, s52, v127
	s_waitcnt vmcnt(11)
	ds_write_b128 v160, v[0:3]
	s_waitcnt vmcnt(10)
	ds_write_b128 v160, v[4:7] offset:8192
	s_waitcnt vmcnt(9)
	ds_write_b128 v160, v[16:19] offset:16384
	s_waitcnt vmcnt(8)
	ds_write_b128 v160, v[28:31] offset:24576
	s_waitcnt vmcnt(0)
	s_waitcnt lgkmcnt(0)
	s_barrier
	v_subrev_u32_e32 v164, s52, v129
	v_subrev_u32_e32 v165, s52, v130
	v_subrev_u32_e32 v166, s52, v131
	v_subrev_u32_e32 v167, s52, v132
	v_subrev_u32_e32 v168, s52, v133
	v_subrev_u32_e32 v169, s52, v134
	v_subrev_u32_e32 v170, s52, v135
	v_subrev_u32_e32 v171, s52, v136
	v_subrev_u32_e32 v172, s52, v137
	v_subrev_u32_e32 v173, s52, v138
	v_subrev_u32_e32 v174, s52, v139
	v_subrev_u32_e32 v175, s52, v140
	v_subrev_u32_e32 v176, s52, v141
	v_add_u32_e32 v177, s16, v142
	v_add_u32_e32 v178, s16, v143
	v_add_u32_e32 v179, s16, v144
	v_add_u32_e32 v180, s16, v145
	v_add_u32_e32 v181, s16, v146
	v_add_u32_e32 v182, s16, v147
	v_add_u32_e32 v183, s16, v148
	v_add_u32_e32 v184, s16, v149
	v_add_u32_e32 v185, s16, v150
	v_add_u32_e32 v186, s16, v151
	v_add_u32_e32 v187, s16, v152
	v_add_u32_e32 v188, s16, v153
	v_add_u32_e32 v189, s16, v154
	v_add_u32_e32 v190, s16, v155
	v_add_u32_e32 v191, s16, v156
	v_add_u32_e32 v192, s16, v157
	s_mov_b32 s49, 2
	v_mov_b64_e32 v[76:77], v[64:65]
	v_mov_b64_e32 v[72:73], v[64:65]
	v_mov_b64_e32 v[68:69], v[64:65]
	v_mov_b64_e32 v[62:63], v[66:67]
	v_mov_b64_e32 v[58:59], v[66:67]
	v_mov_b64_e32 v[54:55], v[66:67]
	v_mov_b64_e32 v[46:47], v[66:67]
	v_mov_b64_e32 v[102:103], v[84:85]
	s_branch .LBB0_301

.LBB0_305:
	s_cmp_ge_u32 s49, s28
	s_cbranch_scc1 .Lna_tail0
	s_nop 0
	v_lshl_add_u64 v[0:1], v[104:105], 0, v[98:99]
	s_nop 0
	v_add_co_u32_e32 v4, vcc, 0x8ca0000, v0
	s_nop 0
	v_lshl_add_u64 v[16:17], v[104:105], 0, v[100:101]
	v_addc_co_u32_e32 v5, vcc, 0, v1, vcc
	s_nop 0
	v_add_co_u32_e32 v28, vcc, 0x8ca0000, v16
	global_load_dwordx4 v[0:3], v[4:5], off offset:1024
	s_nop 0
	global_load_dwordx4 v[4:7], v[4:5], off offset:2048
	v_addc_co_u32_e32 v29, vcc, 0, v17, vcc
	global_load_dwordx4 v[16:19], v[28:29], off offset:1024
	s_nop 0
	global_load_dwordx4 v[28:31], v[28:29], off offset:2048
.LBB0_307:
	s_add_i32 s16, s47, s49
	s_add_i32 s51, s16, -2
	s_cmp_ge_u32 s51, s24
	s_cselect_b64 s[16:17], -1, 0
	s_cmp_lt_u32 s51, s31
	s_cselect_b64 s[52:53], -1, 0
	s_and_b64 s[16:17], s[16:17], s[52:53]
	s_andn2_b64 vcc, exec, s[16:17]
	s_cbranch_vccnz .LBB0_309
	v_add_u32_e32 v85, v118, v107
	ds_read_b128 v[194:197], v85
	ds_read_b128 v[202:205], v85 offset:2048
	v_add_u32_e32 v193, v118, v108
	ds_read_b128 v[198:201], v193
	ds_read_b128 v[206:209], v193 offset:2048
	v_add_u32_e32 v210, 0, v192
	v_add_u32_e32 v211, 0, v191
	v_add_u32_e32 v212, 0, v190
	v_add_u32_e32 v85, 0, v187
	s_waitcnt lgkmcnt(3)
	v_mfma_f32_16x16x32_bf16 v[194:197], v[194:197], v[20:23], 0
	v_add_u32_e32 v193, 0, v185
	v_add_u32_e32 v213, 0, v189
	v_add_u32_e32 v214, 0, v188
	s_waitcnt lgkmcnt(1)
	v_mfma_f32_16x16x32_bf16 v[194:197], v[198:201], v[24:27], v[194:197]
	v_add_u32_e32 v215, 0, v186
	ds_read_b32 v198, v210
	ds_read_b32 v199, v211
	ds_read_b32 v200, v212
	ds_read_b32 v210, v213
	ds_read_b32 v211, v214
	ds_read_b32 v85, v85
	ds_read_b32 v212, v215
	ds_read_b32 v193, v193
	v_add_u32_e32 v217, 0, v177
	s_waitcnt lgkmcnt(7)
	v_add_f32_e32 v194, v194, v198
	v_exp_f32_e32 v214, v194
	s_waitcnt lgkmcnt(6)
	v_add_f32_e32 v194, v195, v199
	v_exp_f32_e32 v222, v194
	s_waitcnt lgkmcnt(5)
	v_add_f32_e32 v194, v196, v200
	v_mfma_f32_16x16x32_bf16 v[198:201], v[202:205], v[20:23], 0
	v_exp_f32_e32 v224, v194
	s_waitcnt lgkmcnt(4)
	v_add_f32_e32 v194, v197, v210
	v_exp_f32_e32 v226, v194
	v_mfma_f32_16x16x32_bf16 v[194:197], v[206:209], v[24:27], v[198:201]
	v_add_u32_e32 v215, 0, v178
	s_nop 1
	v_cvt_pk_bf16_f32 v198, v214, v222
	v_cvt_pk_bf16_f32 v199, v224, v226
	s_waitcnt lgkmcnt(2)
	s_nop 1
	v_add_f32_e32 v85, v195, v85
	v_exp_f32_e32 v230, v85
	s_waitcnt lgkmcnt(1)
	v_add_f32_e32 v85, v196, v212
	v_add_f32_e32 v194, v194, v211
	v_exp_f32_e32 v232, v85
	s_waitcnt lgkmcnt(0)
	v_add_f32_e32 v85, v197, v193
	v_add_u32_e32 v193, v119, v111
	v_exp_f32_e32 v228, v194
	ds_read_b64_tr_b16 v[194:195], v193 offset:8192
	ds_read_b64_tr_b16 v[196:197], v193 offset:10240
	v_exp_f32_e32 v234, v85
	v_add_u32_e32 v85, v119, v112
	v_cvt_pk_bf16_f32 v200, v228, v230
	ds_read_b64_tr_b16 v[202:203], v85 offset:8192
	ds_read_b64_tr_b16 v[204:205], v85 offset:10240
	v_cvt_pk_bf16_f32 v201, v232, v234
	v_add_u32_e32 v85, v119, v113
	v_add_u32_e32 v193, v120, v108
	s_waitcnt lgkmcnt(2)
	v_mfma_f32_16x16x32_bf16 v[76:79], v[194:197], v[198:201], v[76:79]
	ds_read_b64_tr_b16 v[194:195], v85 offset:8192
	ds_read_b64_tr_b16 v[196:197], v85 offset:10240
	v_add_u32_e32 v85, v119, v114
	s_waitcnt lgkmcnt(2)
	v_mfma_f32_16x16x32_bf16 v[64:67], v[202:205], v[198:201], v[64:67]
	ds_read_b64_tr_b16 v[202:203], v85 offset:8192
	ds_read_b64_tr_b16 v[204:205], v85 offset:10240
	v_add_u32_e32 v85, v120, v107
	ds_read_b128 v[206:209], v85 offset:2048
	s_waitcnt lgkmcnt(3)
	v_mfma_f32_16x16x32_bf16 v[72:75], v[194:197], v[198:201], v[72:75]
	ds_read_b128 v[194:197], v85
	ds_read_b128 v[210:213], v193
	ds_read_b128 v[218:221], v193 offset:2048
	v_add_u32_e32 v85, 0, v184
	s_waitcnt lgkmcnt(2)
	v_mfma_f32_16x16x32_bf16 v[194:197], v[194:197], v[36:39], 0
	v_add_u32_e32 v193, 0, v183
	s_waitcnt lgkmcnt(1)
	v_mfma_f32_16x16x32_bf16 v[194:197], v[210:213], v[40:43], v[194:197]
	v_add_u32_e32 v210, 0, v182
	v_add_u32_e32 v211, 0, v181
	v_add_u32_e32 v212, 0, v180
	v_add_u32_e32 v213, 0, v179
	ds_read_b32 v85, v85
	ds_read_b32 v193, v193
	ds_read_b32 v210, v210
	ds_read_b32 v211, v211
	ds_read_b32 v212, v212
	ds_read_b32 v213, v213
	ds_read_b32 v233, v215
	ds_read_b32 v217, v217
	s_waitcnt lgkmcnt(7)
	v_add_f32_e32 v85, v194, v85
	v_exp_f32_e32 v215, v85
	s_waitcnt lgkmcnt(6)
	v_add_f32_e32 v85, v195, v193
	v_exp_f32_e32 v223, v85
	v_mfma_f32_16x16x32_bf16 v[68:71], v[202:205], v[198:201], v[68:71]
	v_add_f32_e64 v194, v214, 0
	v_add_f32_e64 v195, v215, 0
	s_waitcnt lgkmcnt(5)
	v_add_f32_e32 v85, v196, v210
	v_pk_add_f32 v[202:203], v[194:195], v[222:223]
	v_mfma_f32_16x16x32_bf16 v[198:201], v[206:209], v[36:39], 0
	v_exp_f32_e32 v225, v85
	s_waitcnt lgkmcnt(4)
	v_add_f32_e32 v85, v197, v211
	v_exp_f32_e32 v227, v85
	v_mfma_f32_16x16x32_bf16 v[194:197], v[218:221], v[40:43], v[198:201]
	v_add_f32_e64 v210, v202, v224
	v_add_f32_e64 v211, v203, v225
	s_waitcnt lgkmcnt(3)
	s_nop 4
	v_add_f32_e32 v85, v194, v212
	v_exp_f32_e32 v229, v85
	s_waitcnt lgkmcnt(2)
	v_add_f32_e32 v85, v195, v213
	v_exp_f32_e32 v231, v85
	s_waitcnt lgkmcnt(1)
	v_add_f32_e32 v85, v196, v233
	v_exp_f32_e32 v233, v85
	s_waitcnt lgkmcnt(0)
	v_add_f32_e32 v85, v197, v217
	v_exp_f32_e32 v235, v85
	v_add_u32_e32 v85, v121, v111
	ds_read_b64_tr_b16 v[198:199], v85 offset:8192
	ds_read_b64_tr_b16 v[200:201], v85 offset:10240
	v_add_u32_e32 v85, v121, v112
	ds_read_b64_tr_b16 v[202:203], v85 offset:8192
	ds_read_b64_tr_b16 v[204:205], v85 offset:10240
	v_add_u32_e32 v85, v121, v113
	v_cvt_pk_bf16_f32 v194, v215, v223
	v_cvt_pk_bf16_f32 v195, v225, v227
	v_cvt_pk_bf16_f32 v196, v229, v231
	v_cvt_pk_bf16_f32 v197, v233, v235
	ds_read_b64_tr_b16 v[206:207], v85 offset:8192
	ds_read_b64_tr_b16 v[208:209], v85 offset:10240
	v_add_u32_e32 v85, v121, v114
	s_waitcnt lgkmcnt(4)
	v_mfma_f32_16x16x32_bf16 v[60:63], v[198:201], v[194:197], v[60:63]
	ds_read_b64_tr_b16 v[198:199], v85 offset:8192
	ds_read_b64_tr_b16 v[200:201], v85 offset:10240
	s_waitcnt lgkmcnt(4)
	v_mfma_f32_16x16x32_bf16 v[56:59], v[202:205], v[194:197], v[56:59]
	v_add_f32_e64 v202, v210, v226
	v_add_f32_e64 v203, v211, v227
	v_pk_add_f32 v[202:203], v[202:203], v[228:229]
	s_waitcnt lgkmcnt(2)
	v_mfma_f32_16x16x32_bf16 v[52:55], v[206:209], v[194:197], v[52:55]
	v_add_f32_e64 v202, v202, v230
	v_add_f32_e64 v203, v203, v231
	v_pk_add_f32 v[202:203], v[202:203], v[232:233]
	s_waitcnt lgkmcnt(0)
	v_mfma_f32_16x16x32_bf16 v[44:47], v[198:201], v[194:197], v[44:47]
	v_add_f32_e64 v202, v202, v234
	v_add_f32_e64 v203, v203, v235
	v_pk_add_f32 v[102:103], v[202:203], v[102:103]
.LBB0_309:
	s_add_i32 s51, s49, -1
	s_cmp_ge_u32 s51, s28
	s_cbranch_scc1 .LBB0_311
	s_waitcnt vmcnt(4)
	ds_write_b128 v160, v[8:11] offset:32768
	ds_write_b128 v160, v[12:15] offset:40960
	ds_write_b128 v160, v[32:35] offset:49152
	ds_write_b128 v160, v[48:51] offset:57344

.LBB0_312:
	s_cmp_ge_i32 s50, s29
	s_cbranch_scc1 .Lna_tail1
	s_nop 0
	v_lshl_add_u64 v[8:9], v[104:105], 0, v[98:99]
	s_nop 0
	v_add_co_u32_e32 v12, vcc, 0x8cf0000, v8
	s_nop 0
	v_lshl_add_u64 v[32:33], v[104:105], 0, v[100:101]
	v_addc_co_u32_e32 v13, vcc, 0, v9, vcc
	s_nop 0
	v_add_co_u32_e32 v48, vcc, 0x8cf0000, v32
	global_load_dwordx4 v[8:11], v[12:13], off offset:1024
	s_nop 0
	global_load_dwordx4 v[12:15], v[12:13], off offset:2048
	v_addc_co_u32_e32 v49, vcc, 0, v33, vcc
	global_load_dwordx4 v[32:35], v[48:49], off offset:1024
	s_nop 0
	global_load_dwordx4 v[48:51], v[48:49], off offset:2048
.LBB0_314:
	s_add_i32 s16, s47, s49
	s_add_i32 s51, s16, -1
	s_cmp_ge_u32 s51, s24
	s_cselect_b64 s[16:17], -1, 0
	s_cmp_lt_u32 s51, s31
	s_cselect_b64 s[52:53], -1, 0
	s_and_b64 s[16:17], s[16:17], s[52:53]
	s_andn2_b64 vcc, exec, s[16:17]
	s_cbranch_vccnz .LBB0_316
	v_add_u32_e32 v85, v118, v107
	ds_read_b128 v[194:197], v85 offset:32768
	ds_read_b128 v[202:205], v85 offset:34816
	v_add_u32_e32 v193, v118, v108
	ds_read_b128 v[198:201], v193 offset:32768
	ds_read_b128 v[206:209], v193 offset:34816
	v_add_u32_e32 v210, s48, v176
	v_add_u32_e32 v211, s48, v175
	v_add_u32_e32 v213, s48, v173
	v_add_u32_e32 v85, s48, v171
	s_waitcnt lgkmcnt(3)
	v_mfma_f32_16x16x32_bf16 v[194:197], v[194:197], v[20:23], 0
	v_add_u32_e32 v215, s48, v170
	v_add_u32_e32 v193, s48, v169
	v_add_u32_e32 v212, s48, v174
	s_waitcnt lgkmcnt(1)
	v_mfma_f32_16x16x32_bf16 v[194:197], v[198:201], v[24:27], v[194:197]
	v_add_u32_e32 v214, s48, v172
	ds_read_b32 v198, v210
	ds_read_b32 v199, v211
	ds_read_b32 v200, v212
	ds_read_b32 v211, v213
	ds_read_b32 v213, v214
	ds_read_b32 v85, v85
	ds_read_b32 v215, v215
	ds_read_b32 v193, v193
	s_waitcnt lgkmcnt(7)
	v_add_f32_e32 v194, v194, v198
	v_exp_f32_e32 v210, v194
	s_waitcnt lgkmcnt(6)
	v_add_f32_e32 v194, v195, v199
	v_exp_f32_e32 v212, v194
	s_waitcnt lgkmcnt(5)
	v_add_f32_e32 v194, v196, v200
	v_mfma_f32_16x16x32_bf16 v[198:201], v[202:205], v[20:23], 0
	v_exp_f32_e32 v214, v194
	s_waitcnt lgkmcnt(4)
	v_add_f32_e32 v194, v197, v211
	v_exp_f32_e32 v218, v194
	v_mfma_f32_16x16x32_bf16 v[194:197], v[206:209], v[24:27], v[198:201]
	v_cvt_pk_bf16_f32 v202, v210, v212
	v_add_u32_e32 v211, s48, v162
	v_cvt_pk_bf16_f32 v203, v214, v218
	s_waitcnt lgkmcnt(2)
	s_nop 3
	v_add_f32_e32 v85, v195, v85
	v_exp_f32_e32 v222, v85
	s_waitcnt lgkmcnt(1)
	v_add_f32_e32 v85, v196, v215
	v_add_f32_e32 v194, v194, v213
	v_exp_f32_e32 v224, v85
	s_waitcnt lgkmcnt(0)
	v_add_f32_e32 v85, v197, v193
	v_add_u32_e32 v193, v119, v111
	v_exp_f32_e32 v220, v194
	ds_read_b64_tr_b16 v[194:195], v193 offset:40960
	ds_read_b64_tr_b16 v[196:197], v193 offset:43008
	v_exp_f32_e32 v226, v85
	v_add_u32_e32 v85, v119, v112
	ds_read_b64_tr_b16 v[198:199], v85 offset:40960
	ds_read_b64_tr_b16 v[200:201], v85 offset:43008
	v_cvt_pk_bf16_f32 v204, v220, v222
	v_cvt_pk_bf16_f32 v205, v224, v226
	v_add_u32_e32 v85, v119, v113
	v_add_u32_e32 v193, v120, v108
	s_waitcnt lgkmcnt(2)
	v_mfma_f32_16x16x32_bf16 v[76:79], v[194:197], v[202:205], v[76:79]
	ds_read_b64_tr_b16 v[194:195], v85 offset:40960
	ds_read_b64_tr_b16 v[196:197], v85 offset:43008
	v_add_u32_e32 v85, v119, v114
	v_add_u32_e32 v213, s48, v161
	s_waitcnt lgkmcnt(2)
	v_mfma_f32_16x16x32_bf16 v[64:67], v[198:201], v[202:205], v[64:67]
	ds_read_b64_tr_b16 v[198:199], v85 offset:40960
	ds_read_b64_tr_b16 v[200:201], v85 offset:43008
	v_add_u32_e32 v85, v120, v107
	s_waitcnt lgkmcnt(2)
	v_mfma_f32_16x16x32_bf16 v[72:75], v[194:197], v[202:205], v[72:75]
	ds_read_b128 v[194:197], v85 offset:32768
	s_waitcnt lgkmcnt(1)
	v_mfma_f32_16x16x32_bf16 v[68:71], v[198:201], v[202:205], v[68:71]
	ds_read_b128 v[198:201], v85 offset:34816
	ds_read_b128 v[202:205], v193 offset:32768
	ds_read_b128 v[206:209], v193 offset:34816
	v_add_u32_e32 v85, s48, v168
	s_waitcnt lgkmcnt(3)
	v_mfma_f32_16x16x32_bf16 v[194:197], v[194:197], v[36:39], 0
	v_add_u32_e32 v193, s48, v167
	s_waitcnt lgkmcnt(1)
	v_mfma_f32_16x16x32_bf16 v[194:197], v[202:205], v[40:43], v[194:197]
	v_add_u32_e32 v202, s48, v166
	v_add_u32_e32 v203, s48, v165
	v_add_u32_e32 v204, s48, v164
	v_add_u32_e32 v205, s48, v163
	ds_read_b32 v85, v85
	ds_read_b32 v193, v193
	ds_read_b32 v202, v202
	ds_read_b32 v203, v203
	ds_read_b32 v204, v204
	ds_read_b32 v205, v205
	ds_read_b32 v217, v211
	ds_read_b32 v227, v213
	v_mfma_f32_16x16x32_bf16 v[198:201], v[198:201], v[36:39], 0
	s_waitcnt lgkmcnt(7)
	v_add_f32_e32 v85, v194, v85
	v_exp_f32_e32 v211, v85
	s_waitcnt lgkmcnt(6)
	v_add_f32_e32 v85, v195, v193
	v_exp_f32_e32 v213, v85
	s_waitcnt lgkmcnt(5)
	v_add_f32_e32 v85, v196, v202
	v_exp_f32_e32 v215, v85
	s_waitcnt lgkmcnt(4)
	v_add_f32_e32 v85, v197, v203
	v_mfma_f32_16x16x32_bf16 v[194:197], v[206:209], v[40:43], v[198:201]
	v_exp_f32_e32 v219, v85
	s_waitcnt lgkmcnt(3)
	s_nop 5
	v_add_f32_e32 v85, v194, v204
	v_exp_f32_e32 v221, v85
	s_waitcnt lgkmcnt(2)
	v_add_f32_e32 v85, v195, v205
	v_exp_f32_e32 v223, v85
	s_waitcnt lgkmcnt(1)
	v_add_f32_e32 v85, v196, v217
	v_exp_f32_e32 v225, v85
	s_waitcnt lgkmcnt(0)
	v_add_f32_e32 v85, v197, v227
	v_exp_f32_e32 v227, v85
	v_add_u32_e32 v85, v121, v111
	ds_read_b64_tr_b16 v[198:199], v85 offset:40960
	ds_read_b64_tr_b16 v[200:201], v85 offset:43008
	v_pk_add_f32 v[194:195], v[210:211], 0 op_sel_hi:[1,0]
	v_add_u32_e32 v85, v121, v112
	v_pk_add_f32 v[194:195], v[194:195], v[212:213]
	ds_read_b64_tr_b16 v[202:203], v85 offset:40960
	ds_read_b64_tr_b16 v[204:205], v85 offset:43008
	v_add_u32_e32 v85, v121, v113
	v_pk_add_f32 v[228:229], v[194:195], v[214:215]
	v_cvt_pk_bf16_f32 v194, v211, v213
	v_cvt_pk_bf16_f32 v195, v215, v219
	v_cvt_pk_bf16_f32 v196, v221, v223
	v_cvt_pk_bf16_f32 v197, v225, v227
	ds_read_b64_tr_b16 v[206:207], v85 offset:40960
	ds_read_b64_tr_b16 v[208:209], v85 offset:43008
	v_add_u32_e32 v85, v121, v114
	s_waitcnt lgkmcnt(4)
	v_mfma_f32_16x16x32_bf16 v[60:63], v[198:201], v[194:197], v[60:63]
	ds_read_b64_tr_b16 v[198:199], v85 offset:40960
	ds_read_b64_tr_b16 v[200:201], v85 offset:43008
	s_waitcnt lgkmcnt(4)
	v_mfma_f32_16x16x32_bf16 v[56:59], v[202:205], v[194:197], v[56:59]
	v_add_f32_e64 v202, v228, v218
	v_add_f32_e64 v203, v229, v219
	v_pk_add_f32 v[202:203], v[202:203], v[220:221]
	s_waitcnt lgkmcnt(2)
	v_mfma_f32_16x16x32_bf16 v[52:55], v[206:209], v[194:197], v[52:55]
	v_add_f32_e64 v202, v202, v222
	v_add_f32_e64 v203, v203, v223
	v_pk_add_f32 v[202:203], v[202:203], v[224:225]
	s_waitcnt lgkmcnt(0)
	v_mfma_f32_16x16x32_bf16 v[44:47], v[198:201], v[194:197], v[44:47]
	v_add_f32_e64 v202, v202, v226
	v_add_f32_e64 v203, v203, v227
	v_pk_add_f32 v[102:103], v[202:203], v[102:103]
.LBB0_316:
	s_cmp_ge_i32 s50, s30
	s_cbranch_scc1 .LBB0_299
	s_waitcnt vmcnt(4)
	ds_write_b128 v160, v[0:3]
	ds_write_b128 v160, v[4:7] offset:8192
	ds_write_b128 v160, v[16:19] offset:16384
	ds_write_b128 v160, v[28:31] offset:24576
	s_branch .LBB0_299
.Lna_tail0:
	s_waitcnt vmcnt(0)
	s_branch .LBB0_307
